# P1 rotary epilogue: second-half cs-table loads issued with the first half (one load latency per row-group instead of two), on top of P5 4-slice tail
# speedup vs baseline: 1.0046x; 1.0046x over previous
.LBB0_166:
	s_lshl_b32 s23, s6, 8
	s_cmp_gt_i32 s30, 13
	s_cselect_b64 s[34:35], -1, 0
	v_add_u32_e32 v150, s23, v165
	s_mov_b64 s[6:7], -1
	s_and_b64 vcc, exec, s[34:35]
	s_cbranch_vccz .LBB0_176
	v_cmp_lt_i32_e32 vcc, s52, v150
	s_and_saveexec_b64 s[2:3], vcc
	s_xor_b64 s[6:7], exec, s[2:3]
	v_cmp_gt_u32_e32 vcc, s53, v150
	s_nop 1
	v_cndmask_b32_e32 v148, 0, v167, vcc
	s_andn2_saveexec_b64 s[6:7], s[6:7]
	v_mul_hi_i32 v138, v150, s54
	v_lshrrev_b32_e32 v148, 31, v138
	v_ashrrev_i32_e32 v138, 7, v138
	v_add_u32_e32 v138, v138, v148
	v_mul_lo_u32 v138, v138, s47
	v_sub_u32_e32 v148, v150, v138
	s_or_b64 exec, exec, s[6:7]
	v_lshl_add_u32 v138, s30, 8, v169
	v_ashrrev_i32_e32 v149, 31, v148
	v_lshlrev_b64 v[148:149], 10, v[148:149]
	v_cmp_gt_i32_e32 vcc, s55, v138
	v_mov_b32_e32 v152, v124
	v_mov_b32_e32 v153, v125
	v_mov_b32_e32 v154, v126
	v_mov_b32_e32 v155, v127
	v_mov_b32_e32 v156, v120
	v_mov_b32_e32 v157, v121
	v_mov_b32_e32 v158, v122
	v_mov_b32_e32 v159, v123
	s_and_saveexec_b64 s[6:7], vcc
	s_cbranch_execz .LBB0_173
	v_lshl_add_u64 v[152:153], v[140:141], 0, v[148:149]
	global_load_dwordx4 v[156:159], v[152:153], off offset:16
	s_nop 0
	global_load_dwordx4 v[152:155], v[152:153], off
	v_or_b32_e32 v200, 0x80, v138
	v_and_b32_e32 v200, 0xf8, v200
	v_mov_b32_e32 v201, 0
	v_lshlrev_b32_e32 v200, 2, v200
	v_lshl_add_u64 v[202:203], s[14:15], 0, v[148:149]
	v_lshl_add_u64 v[202:203], v[202:203], 0, v[200:201]
	global_load_dwordx4 v[192:195], v[202:203], off offset:16
	global_load_dwordx4 v[188:191], v[202:203], off
	v_cmp_lt_i32_e32 vcc, s60, v138
	s_waitcnt vmcnt(2)
	v_pk_mul_f32 v[182:183], v[124:125], v[152:153] op_sel:[1,1] op_sel_hi:[1,0]
	s_nop 0
	v_pk_fma_f32 v[184:185], v[124:125], v[152:153], v[182:183] neg_lo:[0,0,1] neg_hi:[0,0,1]
	v_pk_fma_f32 v[152:153], v[124:125], v[152:153], v[182:183] op_sel_hi:[0,1,1]
	v_mov_b32_e32 v182, v127
	v_cndmask_b32_e32 v160, 1.0, v181, vcc
	v_mov_b32_e32 v185, v153
	v_pk_mul_f32 v[182:183], v[182:183], v[154:155] op_sel:[0,1] op_sel_hi:[0,0]
	v_pk_mul_f32 v[152:153], v[160:161], v[184:185] op_sel_hi:[0,1]
	v_pk_fma_f32 v[184:185], v[126:127], v[154:155], v[182:183] neg_lo:[0,0,1] neg_hi:[0,0,1]
	v_pk_fma_f32 v[154:155], v[126:127], v[154:155], v[182:183] op_sel_hi:[0,1,1]
	v_mov_b32_e32 v185, v155
	v_pk_mul_f32 v[182:183], v[120:121], v[156:157] op_sel:[1,1] op_sel_hi:[1,0]
	v_pk_mul_f32 v[154:155], v[160:161], v[184:185] op_sel_hi:[0,1]
	v_pk_fma_f32 v[184:185], v[120:121], v[156:157], v[182:183] neg_lo:[0,0,1] neg_hi:[0,0,1]
	v_pk_fma_f32 v[156:157], v[120:121], v[156:157], v[182:183] op_sel_hi:[0,1,1]
	v_mov_b32_e32 v182, v123
	v_mov_b32_e32 v185, v157
	v_pk_mul_f32 v[182:183], v[182:183], v[158:159] op_sel:[0,1] op_sel_hi:[0,0]
	v_pk_mul_f32 v[156:157], v[160:161], v[184:185] op_sel_hi:[0,1]
	v_pk_fma_f32 v[184:185], v[122:123], v[158:159], v[182:183] neg_lo:[0,0,1] neg_hi:[0,0,1]
	v_pk_fma_f32 v[158:159], v[122:123], v[158:159], v[182:183] op_sel_hi:[0,1,1]
	v_mov_b32_e32 v185, v159
	v_pk_mul_f32 v[158:159], v[160:161], v[184:185] op_sel_hi:[0,1]
.LBB0_173:
	s_or_b64 exec, exec, s[6:7]
	v_ashrrev_i32_e32 v151, 31, v150
	v_lshlrev_b64 v[160:161], 13, v[150:151]
	v_cvt_pk_bf16_f32 v182, v152, v153
	v_lshl_add_u64 v[152:153], s[12:13], 0, v[160:161]
	v_or_b32_e32 v151, 0x80, v138
	v_cvt_pk_bf16_f32 v183, v154, v155
	v_cvt_pk_bf16_f32 v184, v156, v157
	v_cvt_pk_bf16_f32 v185, v158, v159
	v_lshl_add_u64 v[152:153], v[138:139], 1, v[152:153]
	v_cmp_gt_i32_e32 vcc, s55, v151
	v_mov_b32_e32 v154, v116
	v_mov_b32_e32 v155, v117
	v_mov_b32_e32 v156, v118
	v_mov_b32_e32 v157, v119
	v_mov_b32_e32 v158, v112
	v_mov_b32_e32 v159, v113
	v_mov_b32_e32 v160, v114
	v_mov_b32_e32 v161, v115
	global_store_dwordx4 v[152:153], v[182:185], off
	s_and_saveexec_b64 s[6:7], vcc
	s_cbranch_execz .LBB0_175
	v_and_b32_e32 v138, 0xf8, v151
	v_lshl_add_u64 v[148:149], s[14:15], 0, v[148:149]
	v_lshlrev_b32_e32 v138, 2, v138
	v_lshl_add_u64 v[148:149], v[148:149], 0, v[138:139]
	v_cmp_lt_i32_e32 vcc, s60, v151
	s_waitcnt vmcnt(1)
	v_mov_b32_e32 v158, v192
	v_mov_b32_e32 v159, v193
	v_mov_b32_e32 v160, v194
	v_mov_b32_e32 v161, v195
	v_mov_b32_e32 v154, v188
	v_mov_b32_e32 v155, v189
	v_mov_b32_e32 v156, v190
	v_mov_b32_e32 v157, v191
	v_pk_mul_f32 v[148:149], v[116:117], v[154:155] op_sel:[1,1] op_sel_hi:[1,0]
	s_nop 0
	v_pk_fma_f32 v[182:183], v[116:117], v[154:155], v[148:149] neg_lo:[0,0,1] neg_hi:[0,0,1]
	v_pk_fma_f32 v[148:149], v[116:117], v[154:155], v[148:149] op_sel_hi:[0,1,1]
	v_mov_b32_e32 v148, v119
	v_cndmask_b32_e32 v138, 1.0, v181, vcc
	v_mov_b32_e32 v183, v149
	v_pk_mul_f32 v[148:149], v[148:149], v[156:157] op_sel:[0,1] op_sel_hi:[0,0]
	v_pk_mul_f32 v[154:155], v[138:139], v[182:183] op_sel_hi:[0,1]
	v_pk_fma_f32 v[182:183], v[118:119], v[156:157], v[148:149] neg_lo:[0,0,1] neg_hi:[0,0,1]
	v_pk_fma_f32 v[148:149], v[118:119], v[156:157], v[148:149] op_sel_hi:[0,1,1]
	v_mov_b32_e32 v183, v149
	v_pk_mul_f32 v[148:149], v[112:113], v[158:159] op_sel:[1,1] op_sel_hi:[1,0]
	v_pk_mul_f32 v[156:157], v[138:139], v[182:183] op_sel_hi:[0,1]
	v_pk_fma_f32 v[182:183], v[112:113], v[158:159], v[148:149] neg_lo:[0,0,1] neg_hi:[0,0,1]
	v_pk_fma_f32 v[148:149], v[112:113], v[158:159], v[148:149] op_sel_hi:[0,1,1]
	v_mov_b32_e32 v148, v115
	v_mov_b32_e32 v183, v149
	v_pk_mul_f32 v[148:149], v[148:149], v[160:161] op_sel:[0,1] op_sel_hi:[0,0]
	v_pk_mul_f32 v[158:159], v[138:139], v[182:183] op_sel_hi:[0,1]
	v_pk_fma_f32 v[182:183], v[114:115], v[160:161], v[148:149] neg_lo:[0,0,1] neg_hi:[0,0,1]
	v_pk_fma_f32 v[148:149], v[114:115], v[160:161], v[148:149] op_sel_hi:[0,1,1]
	v_mov_b32_e32 v183, v149
	v_pk_mul_f32 v[160:161], v[138:139], v[182:183] op_sel_hi:[0,1]
.LBB0_175:
	s_waitcnt vmcnt(1)
	s_or_b64 exec, exec, s[6:7]
	s_mov_b64 s[6:7], 0
	v_cvt_pk_bf16_f32 v154, v154, v155
	v_cvt_pk_bf16_f32 v155, v156, v157
	v_cvt_pk_bf16_f32 v156, v158, v159
	v_cvt_pk_bf16_f32 v157, v160, v161
	global_store_dwordx4 v[152:153], v[154:157], off offset:256

.LBB0_197:
	v_cmp_lt_i32_e32 vcc, s52, v112
	s_and_saveexec_b64 s[2:3], vcc
	s_xor_b64 s[34:35], exec, s[2:3]
	v_cmp_gt_u32_e32 vcc, s53, v112
	s_nop 1
	v_cndmask_b32_e32 v114, 0, v167, vcc
	s_andn2_saveexec_b64 s[34:35], s[34:35]
	v_mul_hi_i32 v113, v112, s54
	v_lshrrev_b32_e32 v114, 31, v113
	v_ashrrev_i32_e32 v113, 7, v113
	v_add_u32_e32 v113, v113, v114
	v_mul_lo_u32 v113, v113, s47
	v_sub_u32_e32 v114, v112, v113
	s_or_b64 exec, exec, s[34:35]
	v_lshl_add_u32 v138, s30, 8, v169
	v_ashrrev_i32_e32 v115, 31, v114
	v_lshlrev_b64 v[114:115], 10, v[114:115]
	v_cmp_gt_i32_e32 vcc, s55, v138
	v_mov_b32_e32 v116, v108
	v_mov_b32_e32 v117, v109
	v_mov_b32_e32 v118, v110
	v_mov_b32_e32 v119, v111
	v_mov_b32_e32 v120, v104
	v_mov_b32_e32 v121, v105
	v_mov_b32_e32 v122, v106
	v_mov_b32_e32 v123, v107
	s_and_saveexec_b64 s[34:35], vcc
	s_cbranch_execz .LBB0_203
	v_lshl_add_u64 v[116:117], v[140:141], 0, v[114:115]
	global_load_dwordx4 v[120:123], v[116:117], off offset:16
	s_nop 0
	global_load_dwordx4 v[116:119], v[116:117], off
	v_or_b32_e32 v200, 0x80, v138
	v_and_b32_e32 v200, 0xf8, v200
	v_mov_b32_e32 v201, 0
	v_lshlrev_b32_e32 v200, 2, v200
	v_lshl_add_u64 v[202:203], s[14:15], 0, v[114:115]
	v_lshl_add_u64 v[202:203], v[202:203], 0, v[200:201]
	global_load_dwordx4 v[192:195], v[202:203], off offset:16
	global_load_dwordx4 v[188:191], v[202:203], off
	v_cmp_lt_i32_e32 vcc, s60, v138
	s_waitcnt vmcnt(2)
	v_pk_mul_f32 v[126:127], v[108:109], v[116:117] op_sel:[1,1] op_sel_hi:[1,0]
	s_nop 0
	v_pk_fma_f32 v[150:151], v[108:109], v[116:117], v[126:127] neg_lo:[0,0,1] neg_hi:[0,0,1]
	v_pk_fma_f32 v[116:117], v[108:109], v[116:117], v[126:127] op_sel_hi:[0,1,1]
	v_mov_b32_e32 v126, v111
	v_cndmask_b32_e32 v124, 1.0, v181, vcc
	v_mov_b32_e32 v151, v117
	v_pk_mul_f32 v[126:127], v[126:127], v[118:119] op_sel:[0,1] op_sel_hi:[0,0]
	v_pk_mul_f32 v[116:117], v[124:125], v[150:151] op_sel_hi:[0,1]
	v_pk_fma_f32 v[150:151], v[110:111], v[118:119], v[126:127] neg_lo:[0,0,1] neg_hi:[0,0,1]
	v_pk_fma_f32 v[118:119], v[110:111], v[118:119], v[126:127] op_sel_hi:[0,1,1]
	v_mov_b32_e32 v151, v119
	v_pk_mul_f32 v[126:127], v[104:105], v[120:121] op_sel:[1,1] op_sel_hi:[1,0]
	v_pk_mul_f32 v[118:119], v[124:125], v[150:151] op_sel_hi:[0,1]
	v_pk_fma_f32 v[150:151], v[104:105], v[120:121], v[126:127] neg_lo:[0,0,1] neg_hi:[0,0,1]
	v_pk_fma_f32 v[120:121], v[104:105], v[120:121], v[126:127] op_sel_hi:[0,1,1]
	v_mov_b32_e32 v126, v107
	v_mov_b32_e32 v151, v121
	v_pk_mul_f32 v[126:127], v[126:127], v[122:123] op_sel:[0,1] op_sel_hi:[0,0]
	v_pk_mul_f32 v[120:121], v[124:125], v[150:151] op_sel_hi:[0,1]
	v_pk_fma_f32 v[150:151], v[106:107], v[122:123], v[126:127] neg_lo:[0,0,1] neg_hi:[0,0,1]
	v_pk_fma_f32 v[122:123], v[106:107], v[122:123], v[126:127] op_sel_hi:[0,1,1]
	v_mov_b32_e32 v151, v123
	v_pk_mul_f32 v[122:123], v[124:125], v[150:151] op_sel_hi:[0,1]
.LBB0_203:
	s_or_b64 exec, exec, s[34:35]
	v_ashrrev_i32_e32 v113, 31, v112
	v_lshlrev_b64 v[150:151], 13, v[112:113]
	v_cvt_pk_bf16_f32 v124, v116, v117
	v_lshl_add_u64 v[116:117], s[12:13], 0, v[150:151]
	v_cvt_pk_bf16_f32 v125, v118, v119
	v_lshl_add_u64 v[116:117], v[138:139], 1, v[116:117]
	v_or_b32_e32 v113, 0x80, v138
	v_cvt_pk_bf16_f32 v126, v120, v121
	v_cvt_pk_bf16_f32 v127, v122, v123
	global_store_dwordx4 v[116:117], v[124:127], off
	v_cmp_gt_i32_e32 vcc, s55, v113
	v_mov_b32_e32 v118, v100
	v_mov_b32_e32 v119, v101
	v_mov_b32_e32 v120, v102
	v_mov_b32_e32 v121, v103
	v_mov_b32_e32 v122, v96
	v_mov_b32_e32 v123, v97
	v_mov_b32_e32 v124, v98
	v_mov_b32_e32 v125, v99
	s_and_saveexec_b64 s[34:35], vcc
	s_cbranch_execz .LBB0_205
	v_and_b32_e32 v118, 0xf8, v113
	v_lshl_add_u64 v[114:115], s[14:15], 0, v[114:115]
	v_lshlrev_b32_e32 v138, 2, v118
	v_lshl_add_u64 v[114:115], v[114:115], 0, v[138:139]
	v_cmp_lt_i32_e32 vcc, s60, v113
	s_waitcnt vmcnt(1)
	v_mov_b32_e32 v122, v192
	v_mov_b32_e32 v123, v193
	v_mov_b32_e32 v124, v194
	v_mov_b32_e32 v125, v195
	v_mov_b32_e32 v118, v188
	v_mov_b32_e32 v119, v189
	v_mov_b32_e32 v120, v190
	v_mov_b32_e32 v121, v191
	v_pk_mul_f32 v[126:127], v[100:101], v[118:119] op_sel:[1,1] op_sel_hi:[1,0]
	s_nop 0
	v_pk_fma_f32 v[150:151], v[100:101], v[118:119], v[126:127] neg_lo:[0,0,1] neg_hi:[0,0,1]
	v_pk_fma_f32 v[118:119], v[100:101], v[118:119], v[126:127] op_sel_hi:[0,1,1]
	v_mov_b32_e32 v126, v103
	v_cndmask_b32_e32 v114, 1.0, v181, vcc
	v_mov_b32_e32 v151, v119
	v_pk_mul_f32 v[126:127], v[126:127], v[120:121] op_sel:[0,1] op_sel_hi:[0,0]
	v_pk_mul_f32 v[118:119], v[114:115], v[150:151] op_sel_hi:[0,1]
	v_pk_fma_f32 v[150:151], v[102:103], v[120:121], v[126:127] neg_lo:[0,0,1] neg_hi:[0,0,1]
	v_pk_fma_f32 v[120:121], v[102:103], v[120:121], v[126:127] op_sel_hi:[0,1,1]
	v_mov_b32_e32 v151, v121
	v_pk_mul_f32 v[126:127], v[96:97], v[122:123] op_sel:[1,1] op_sel_hi:[1,0]
	v_pk_mul_f32 v[120:121], v[114:115], v[150:151] op_sel_hi:[0,1]
	v_pk_fma_f32 v[150:151], v[96:97], v[122:123], v[126:127] neg_lo:[0,0,1] neg_hi:[0,0,1]
	v_pk_fma_f32 v[122:123], v[96:97], v[122:123], v[126:127] op_sel_hi:[0,1,1]
	v_mov_b32_e32 v126, v99
	v_mov_b32_e32 v151, v123
	v_pk_mul_f32 v[126:127], v[126:127], v[124:125] op_sel:[0,1] op_sel_hi:[0,0]
	v_pk_mul_f32 v[122:123], v[114:115], v[150:151] op_sel_hi:[0,1]
	v_pk_fma_f32 v[150:151], v[98:99], v[124:125], v[126:127] neg_lo:[0,0,1] neg_hi:[0,0,1]
	v_pk_fma_f32 v[124:125], v[98:99], v[124:125], v[126:127] op_sel_hi:[0,1,1]
	v_mov_b32_e32 v151, v125
	v_pk_mul_f32 v[124:125], v[114:115], v[150:151] op_sel_hi:[0,1]
.LBB0_205:
	s_waitcnt vmcnt(1)
	s_or_b64 exec, exec, s[34:35]
	v_cvt_pk_bf16_f32 v118, v118, v119
	v_cvt_pk_bf16_f32 v119, v120, v121
	v_cvt_pk_bf16_f32 v120, v122, v123
	v_cvt_pk_bf16_f32 v121, v124, v125
	global_store_dwordx4 v[116:117], v[118:121], off offset:256
	s_branch .LBB0_184

.LBB0_211:
	v_cmp_lt_i32_e32 vcc, s52, v96
	s_and_saveexec_b64 s[2:3], vcc
	s_xor_b64 s[34:35], exec, s[2:3]
	v_cmp_gt_u32_e32 vcc, s53, v96
	s_nop 1
	v_cndmask_b32_e32 v98, 0, v167, vcc
	s_andn2_saveexec_b64 s[34:35], s[34:35]
	v_mul_hi_i32 v97, v96, s54
	v_lshrrev_b32_e32 v98, 31, v97
	v_ashrrev_i32_e32 v97, 7, v97
	v_add_u32_e32 v97, v97, v98
	v_mul_lo_u32 v97, v97, s47
	v_sub_u32_e32 v98, v96, v97
	s_or_b64 exec, exec, s[34:35]
	v_lshl_add_u32 v138, s30, 8, v169
	v_ashrrev_i32_e32 v99, 31, v98
	v_lshlrev_b64 v[98:99], 10, v[98:99]
	v_cmp_gt_i32_e32 vcc, s55, v138
	v_mov_b32_e32 v100, v92
	v_mov_b32_e32 v101, v93
	v_mov_b32_e32 v102, v94
	v_mov_b32_e32 v103, v95
	v_mov_b32_e32 v104, v88
	v_mov_b32_e32 v105, v89
	v_mov_b32_e32 v106, v90
	v_mov_b32_e32 v107, v91
	s_and_saveexec_b64 s[34:35], vcc
	s_cbranch_execz .LBB0_217
	v_lshl_add_u64 v[100:101], v[140:141], 0, v[98:99]
	global_load_dwordx4 v[104:107], v[100:101], off offset:16
	s_nop 0
	global_load_dwordx4 v[100:103], v[100:101], off
	v_or_b32_e32 v200, 0x80, v138
	v_and_b32_e32 v200, 0xf8, v200
	v_mov_b32_e32 v201, 0
	v_lshlrev_b32_e32 v200, 2, v200
	v_lshl_add_u64 v[202:203], s[14:15], 0, v[98:99]
	v_lshl_add_u64 v[202:203], v[202:203], 0, v[200:201]
	global_load_dwordx4 v[192:195], v[202:203], off offset:16
	global_load_dwordx4 v[188:191], v[202:203], off
	v_cmp_lt_i32_e32 vcc, s60, v138
	s_waitcnt vmcnt(2)
	v_pk_mul_f32 v[110:111], v[92:93], v[100:101] op_sel:[1,1] op_sel_hi:[1,0]
	s_nop 0
	v_pk_fma_f32 v[112:113], v[92:93], v[100:101], v[110:111] neg_lo:[0,0,1] neg_hi:[0,0,1]
	v_pk_fma_f32 v[100:101], v[92:93], v[100:101], v[110:111] op_sel_hi:[0,1,1]
	v_mov_b32_e32 v110, v95
	v_cndmask_b32_e32 v108, 1.0, v181, vcc
	v_mov_b32_e32 v113, v101
	v_pk_mul_f32 v[110:111], v[110:111], v[102:103] op_sel:[0,1] op_sel_hi:[0,0]
	v_pk_mul_f32 v[100:101], v[108:109], v[112:113] op_sel_hi:[0,1]
	v_pk_fma_f32 v[112:113], v[94:95], v[102:103], v[110:111] neg_lo:[0,0,1] neg_hi:[0,0,1]
	v_pk_fma_f32 v[102:103], v[94:95], v[102:103], v[110:111] op_sel_hi:[0,1,1]
	v_mov_b32_e32 v113, v103
	v_pk_mul_f32 v[110:111], v[88:89], v[104:105] op_sel:[1,1] op_sel_hi:[1,0]
	v_pk_mul_f32 v[102:103], v[108:109], v[112:113] op_sel_hi:[0,1]
	v_pk_fma_f32 v[112:113], v[88:89], v[104:105], v[110:111] neg_lo:[0,0,1] neg_hi:[0,0,1]
	v_pk_fma_f32 v[104:105], v[88:89], v[104:105], v[110:111] op_sel_hi:[0,1,1]
	v_mov_b32_e32 v110, v91
	v_mov_b32_e32 v113, v105
	v_pk_mul_f32 v[110:111], v[110:111], v[106:107] op_sel:[0,1] op_sel_hi:[0,0]
	v_pk_mul_f32 v[104:105], v[108:109], v[112:113] op_sel_hi:[0,1]
	v_pk_fma_f32 v[112:113], v[90:91], v[106:107], v[110:111] neg_lo:[0,0,1] neg_hi:[0,0,1]
	v_pk_fma_f32 v[106:107], v[90:91], v[106:107], v[110:111] op_sel_hi:[0,1,1]
	v_mov_b32_e32 v113, v107
	v_pk_mul_f32 v[106:107], v[108:109], v[112:113] op_sel_hi:[0,1]
.LBB0_217:
	s_or_b64 exec, exec, s[34:35]
	v_ashrrev_i32_e32 v97, 31, v96
	v_lshlrev_b64 v[112:113], 13, v[96:97]
	v_cvt_pk_bf16_f32 v108, v100, v101
	v_lshl_add_u64 v[100:101], s[12:13], 0, v[112:113]
	v_cvt_pk_bf16_f32 v109, v102, v103
	v_lshl_add_u64 v[100:101], v[138:139], 1, v[100:101]
	v_or_b32_e32 v97, 0x80, v138
	v_cvt_pk_bf16_f32 v110, v104, v105
	v_cvt_pk_bf16_f32 v111, v106, v107
	global_store_dwordx4 v[100:101], v[108:111], off
	v_cmp_gt_i32_e32 vcc, s55, v97
	v_mov_b32_e32 v102, v84
	v_mov_b32_e32 v103, v85
	v_mov_b32_e32 v104, v86
	v_mov_b32_e32 v105, v87
	v_mov_b32_e32 v106, v80
	v_mov_b32_e32 v107, v81
	v_mov_b32_e32 v108, v82
	v_mov_b32_e32 v109, v83
	s_and_saveexec_b64 s[34:35], vcc
	s_cbranch_execz .LBB0_219
	v_and_b32_e32 v102, 0xf8, v97
	v_lshl_add_u64 v[98:99], s[14:15], 0, v[98:99]
	v_lshlrev_b32_e32 v138, 2, v102
	v_lshl_add_u64 v[98:99], v[98:99], 0, v[138:139]
	v_cmp_lt_i32_e32 vcc, s60, v97
	s_waitcnt vmcnt(1)
	v_mov_b32_e32 v106, v192
	v_mov_b32_e32 v107, v193
	v_mov_b32_e32 v108, v194
	v_mov_b32_e32 v109, v195
	v_mov_b32_e32 v102, v188
	v_mov_b32_e32 v103, v189
	v_mov_b32_e32 v104, v190
	v_mov_b32_e32 v105, v191
	v_pk_mul_f32 v[110:111], v[84:85], v[102:103] op_sel:[1,1] op_sel_hi:[1,0]
	s_nop 0
	v_pk_fma_f32 v[112:113], v[84:85], v[102:103], v[110:111] neg_lo:[0,0,1] neg_hi:[0,0,1]
	v_pk_fma_f32 v[102:103], v[84:85], v[102:103], v[110:111] op_sel_hi:[0,1,1]
	v_mov_b32_e32 v110, v87
	v_cndmask_b32_e32 v98, 1.0, v181, vcc
	v_mov_b32_e32 v113, v103
	v_pk_mul_f32 v[110:111], v[110:111], v[104:105] op_sel:[0,1] op_sel_hi:[0,0]
	v_pk_mul_f32 v[102:103], v[98:99], v[112:113] op_sel_hi:[0,1]
	v_pk_fma_f32 v[112:113], v[86:87], v[104:105], v[110:111] neg_lo:[0,0,1] neg_hi:[0,0,1]
	v_pk_fma_f32 v[104:105], v[86:87], v[104:105], v[110:111] op_sel_hi:[0,1,1]
	v_mov_b32_e32 v113, v105
	v_pk_mul_f32 v[110:111], v[80:81], v[106:107] op_sel:[1,1] op_sel_hi:[1,0]
	v_pk_mul_f32 v[104:105], v[98:99], v[112:113] op_sel_hi:[0,1]
	v_pk_fma_f32 v[112:113], v[80:81], v[106:107], v[110:111] neg_lo:[0,0,1] neg_hi:[0,0,1]
	v_pk_fma_f32 v[106:107], v[80:81], v[106:107], v[110:111] op_sel_hi:[0,1,1]
	v_mov_b32_e32 v110, v83
	v_mov_b32_e32 v113, v107
	v_pk_mul_f32 v[110:111], v[110:111], v[108:109] op_sel:[0,1] op_sel_hi:[0,0]
	v_pk_mul_f32 v[106:107], v[98:99], v[112:113] op_sel_hi:[0,1]
	v_pk_fma_f32 v[112:113], v[82:83], v[108:109], v[110:111] neg_lo:[0,0,1] neg_hi:[0,0,1]
	v_pk_fma_f32 v[108:109], v[82:83], v[108:109], v[110:111] op_sel_hi:[0,1,1]
	v_mov_b32_e32 v113, v109
	v_pk_mul_f32 v[108:109], v[98:99], v[112:113] op_sel_hi:[0,1]
.LBB0_219:
	s_waitcnt vmcnt(1)
	s_or_b64 exec, exec, s[34:35]
	v_cvt_pk_bf16_f32 v102, v102, v103
	v_cvt_pk_bf16_f32 v103, v104, v105
	v_cvt_pk_bf16_f32 v104, v106, v107
	v_cvt_pk_bf16_f32 v105, v108, v109
	global_store_dwordx4 v[100:101], v[102:105], off offset:256
	s_branch .LBB0_186

.LBB0_225:
	v_cmp_lt_i32_e32 vcc, s52, v80
	s_and_saveexec_b64 s[2:3], vcc
	s_xor_b64 s[34:35], exec, s[2:3]
	v_cmp_gt_u32_e32 vcc, s53, v80
	s_nop 1
	v_cndmask_b32_e32 v82, 0, v167, vcc
	s_andn2_saveexec_b64 s[34:35], s[34:35]
	v_mul_hi_i32 v81, v80, s54
	v_lshrrev_b32_e32 v82, 31, v81
	v_ashrrev_i32_e32 v81, 7, v81
	v_add_u32_e32 v81, v81, v82
	v_mul_lo_u32 v81, v81, s47
	v_sub_u32_e32 v82, v80, v81
	s_or_b64 exec, exec, s[34:35]
	v_lshl_add_u32 v138, s30, 8, v169
	v_ashrrev_i32_e32 v83, 31, v82
	v_lshlrev_b64 v[82:83], 10, v[82:83]
	v_cmp_gt_i32_e32 vcc, s55, v138
	v_mov_b32_e32 v84, v76
	v_mov_b32_e32 v85, v77
	v_mov_b32_e32 v86, v78
	v_mov_b32_e32 v87, v79
	v_mov_b32_e32 v88, v72
	v_mov_b32_e32 v89, v73
	v_mov_b32_e32 v90, v74
	v_mov_b32_e32 v91, v75
	s_and_saveexec_b64 s[34:35], vcc
	s_cbranch_execz .LBB0_231
	v_lshl_add_u64 v[84:85], v[140:141], 0, v[82:83]
	global_load_dwordx4 v[88:91], v[84:85], off offset:16
	s_nop 0
	global_load_dwordx4 v[84:87], v[84:85], off
	v_or_b32_e32 v200, 0x80, v138
	v_and_b32_e32 v200, 0xf8, v200
	v_mov_b32_e32 v201, 0
	v_lshlrev_b32_e32 v200, 2, v200
	v_lshl_add_u64 v[202:203], s[14:15], 0, v[82:83]
	v_lshl_add_u64 v[202:203], v[202:203], 0, v[200:201]
	global_load_dwordx4 v[192:195], v[202:203], off offset:16
	global_load_dwordx4 v[188:191], v[202:203], off
	v_cmp_lt_i32_e32 vcc, s60, v138
	s_waitcnt vmcnt(2)
	v_pk_mul_f32 v[94:95], v[76:77], v[84:85] op_sel:[1,1] op_sel_hi:[1,0]
	s_nop 0
	v_pk_fma_f32 v[96:97], v[76:77], v[84:85], v[94:95] neg_lo:[0,0,1] neg_hi:[0,0,1]
	v_pk_fma_f32 v[84:85], v[76:77], v[84:85], v[94:95] op_sel_hi:[0,1,1]
	v_mov_b32_e32 v94, v79
	v_cndmask_b32_e32 v92, 1.0, v181, vcc
	v_mov_b32_e32 v97, v85
	v_pk_mul_f32 v[94:95], v[94:95], v[86:87] op_sel:[0,1] op_sel_hi:[0,0]
	v_pk_mul_f32 v[84:85], v[92:93], v[96:97] op_sel_hi:[0,1]
	v_pk_fma_f32 v[96:97], v[78:79], v[86:87], v[94:95] neg_lo:[0,0,1] neg_hi:[0,0,1]
	v_pk_fma_f32 v[86:87], v[78:79], v[86:87], v[94:95] op_sel_hi:[0,1,1]
	v_mov_b32_e32 v97, v87
	v_pk_mul_f32 v[94:95], v[72:73], v[88:89] op_sel:[1,1] op_sel_hi:[1,0]
	v_pk_mul_f32 v[86:87], v[92:93], v[96:97] op_sel_hi:[0,1]
	v_pk_fma_f32 v[96:97], v[72:73], v[88:89], v[94:95] neg_lo:[0,0,1] neg_hi:[0,0,1]
	v_pk_fma_f32 v[88:89], v[72:73], v[88:89], v[94:95] op_sel_hi:[0,1,1]
	v_mov_b32_e32 v94, v75
	v_mov_b32_e32 v97, v89
	v_pk_mul_f32 v[94:95], v[94:95], v[90:91] op_sel:[0,1] op_sel_hi:[0,0]
	v_pk_mul_f32 v[88:89], v[92:93], v[96:97] op_sel_hi:[0,1]
	v_pk_fma_f32 v[96:97], v[74:75], v[90:91], v[94:95] neg_lo:[0,0,1] neg_hi:[0,0,1]
	v_pk_fma_f32 v[90:91], v[74:75], v[90:91], v[94:95] op_sel_hi:[0,1,1]
	v_mov_b32_e32 v97, v91
	v_pk_mul_f32 v[90:91], v[92:93], v[96:97] op_sel_hi:[0,1]
.LBB0_231:
	s_or_b64 exec, exec, s[34:35]
	v_ashrrev_i32_e32 v81, 31, v80
	v_lshlrev_b64 v[96:97], 13, v[80:81]
	v_cvt_pk_bf16_f32 v92, v84, v85
	v_lshl_add_u64 v[84:85], s[12:13], 0, v[96:97]
	v_cvt_pk_bf16_f32 v93, v86, v87
	v_lshl_add_u64 v[84:85], v[138:139], 1, v[84:85]
	v_or_b32_e32 v81, 0x80, v138
	v_cvt_pk_bf16_f32 v94, v88, v89
	v_cvt_pk_bf16_f32 v95, v90, v91
	global_store_dwordx4 v[84:85], v[92:95], off
	v_cmp_gt_i32_e32 vcc, s55, v81
	v_mov_b32_e32 v86, v68
	v_mov_b32_e32 v87, v69
	v_mov_b32_e32 v88, v70
	v_mov_b32_e32 v89, v71
	v_mov_b32_e32 v90, v64
	v_mov_b32_e32 v91, v65
	v_mov_b32_e32 v92, v66
	v_mov_b32_e32 v93, v67
	s_and_saveexec_b64 s[34:35], vcc
	s_cbranch_execz .LBB0_233
	v_and_b32_e32 v86, 0xf8, v81
	v_lshl_add_u64 v[82:83], s[14:15], 0, v[82:83]
	v_lshlrev_b32_e32 v138, 2, v86
	v_lshl_add_u64 v[82:83], v[82:83], 0, v[138:139]
	v_cmp_lt_i32_e32 vcc, s60, v81
	s_waitcnt vmcnt(1)
	v_mov_b32_e32 v90, v192
	v_mov_b32_e32 v91, v193
	v_mov_b32_e32 v92, v194
	v_mov_b32_e32 v93, v195
	v_mov_b32_e32 v86, v188
	v_mov_b32_e32 v87, v189
	v_mov_b32_e32 v88, v190
	v_mov_b32_e32 v89, v191
	v_pk_mul_f32 v[94:95], v[68:69], v[86:87] op_sel:[1,1] op_sel_hi:[1,0]
	s_nop 0
	v_pk_fma_f32 v[96:97], v[68:69], v[86:87], v[94:95] neg_lo:[0,0,1] neg_hi:[0,0,1]
	v_pk_fma_f32 v[86:87], v[68:69], v[86:87], v[94:95] op_sel_hi:[0,1,1]
	v_mov_b32_e32 v94, v71
	v_cndmask_b32_e32 v82, 1.0, v181, vcc
	v_mov_b32_e32 v97, v87
	v_pk_mul_f32 v[94:95], v[94:95], v[88:89] op_sel:[0,1] op_sel_hi:[0,0]
	v_pk_mul_f32 v[86:87], v[82:83], v[96:97] op_sel_hi:[0,1]
	v_pk_fma_f32 v[96:97], v[70:71], v[88:89], v[94:95] neg_lo:[0,0,1] neg_hi:[0,0,1]
	v_pk_fma_f32 v[88:89], v[70:71], v[88:89], v[94:95] op_sel_hi:[0,1,1]
	v_mov_b32_e32 v97, v89
	v_pk_mul_f32 v[94:95], v[64:65], v[90:91] op_sel:[1,1] op_sel_hi:[1,0]
	v_pk_mul_f32 v[88:89], v[82:83], v[96:97] op_sel_hi:[0,1]
	v_pk_fma_f32 v[96:97], v[64:65], v[90:91], v[94:95] neg_lo:[0,0,1] neg_hi:[0,0,1]
	v_pk_fma_f32 v[90:91], v[64:65], v[90:91], v[94:95] op_sel_hi:[0,1,1]
	v_mov_b32_e32 v94, v67
	v_mov_b32_e32 v97, v91
	v_pk_mul_f32 v[94:95], v[94:95], v[92:93] op_sel:[0,1] op_sel_hi:[0,0]
	v_pk_mul_f32 v[90:91], v[82:83], v[96:97] op_sel_hi:[0,1]
	v_pk_fma_f32 v[96:97], v[66:67], v[92:93], v[94:95] neg_lo:[0,0,1] neg_hi:[0,0,1]
	v_pk_fma_f32 v[92:93], v[66:67], v[92:93], v[94:95] op_sel_hi:[0,1,1]
	v_mov_b32_e32 v97, v93
	v_pk_mul_f32 v[92:93], v[82:83], v[96:97] op_sel_hi:[0,1]
.LBB0_233:
	s_waitcnt vmcnt(1)
	s_or_b64 exec, exec, s[34:35]
	v_cvt_pk_bf16_f32 v86, v86, v87
	v_cvt_pk_bf16_f32 v87, v88, v89
	v_cvt_pk_bf16_f32 v88, v90, v91
	v_cvt_pk_bf16_f32 v89, v92, v93
	global_store_dwordx4 v[84:85], v[86:89], off offset:256
	s_branch .LBB0_188

.LBB0_239:
	v_cmp_lt_i32_e32 vcc, s52, v64
	s_and_saveexec_b64 s[2:3], vcc
	s_xor_b64 s[34:35], exec, s[2:3]
	v_cmp_gt_u32_e32 vcc, s53, v64
	s_nop 1
	v_cndmask_b32_e32 v66, 0, v167, vcc
	s_andn2_saveexec_b64 s[34:35], s[34:35]
	v_mul_hi_i32 v65, v64, s54
	v_lshrrev_b32_e32 v66, 31, v65
	v_ashrrev_i32_e32 v65, 7, v65
	v_add_u32_e32 v65, v65, v66
	v_mul_lo_u32 v65, v65, s47
	v_sub_u32_e32 v66, v64, v65
	s_or_b64 exec, exec, s[34:35]
	v_lshl_add_u32 v138, s30, 8, v169
	v_ashrrev_i32_e32 v67, 31, v66
	v_lshlrev_b64 v[66:67], 10, v[66:67]
	v_cmp_gt_i32_e32 vcc, s55, v138
	v_mov_b32_e32 v68, v60
	v_mov_b32_e32 v69, v61
	v_mov_b32_e32 v70, v62
	v_mov_b32_e32 v71, v63
	v_mov_b32_e32 v72, v56
	v_mov_b32_e32 v73, v57
	v_mov_b32_e32 v74, v58
	v_mov_b32_e32 v75, v59
	s_and_saveexec_b64 s[34:35], vcc
	s_cbranch_execz .LBB0_245
	v_lshl_add_u64 v[68:69], v[140:141], 0, v[66:67]
	global_load_dwordx4 v[72:75], v[68:69], off offset:16
	s_nop 0
	global_load_dwordx4 v[68:71], v[68:69], off
	v_or_b32_e32 v200, 0x80, v138
	v_and_b32_e32 v200, 0xf8, v200
	v_mov_b32_e32 v201, 0
	v_lshlrev_b32_e32 v200, 2, v200
	v_lshl_add_u64 v[202:203], s[14:15], 0, v[66:67]
	v_lshl_add_u64 v[202:203], v[202:203], 0, v[200:201]
	global_load_dwordx4 v[192:195], v[202:203], off offset:16
	global_load_dwordx4 v[188:191], v[202:203], off
	v_cmp_lt_i32_e32 vcc, s60, v138
	s_waitcnt vmcnt(2)
	v_pk_mul_f32 v[78:79], v[60:61], v[68:69] op_sel:[1,1] op_sel_hi:[1,0]
	s_nop 0
	v_pk_fma_f32 v[80:81], v[60:61], v[68:69], v[78:79] neg_lo:[0,0,1] neg_hi:[0,0,1]
	v_pk_fma_f32 v[68:69], v[60:61], v[68:69], v[78:79] op_sel_hi:[0,1,1]
	v_mov_b32_e32 v78, v63
	v_cndmask_b32_e32 v76, 1.0, v181, vcc
	v_mov_b32_e32 v81, v69
	v_pk_mul_f32 v[78:79], v[78:79], v[70:71] op_sel:[0,1] op_sel_hi:[0,0]
	v_pk_mul_f32 v[68:69], v[76:77], v[80:81] op_sel_hi:[0,1]
	v_pk_fma_f32 v[80:81], v[62:63], v[70:71], v[78:79] neg_lo:[0,0,1] neg_hi:[0,0,1]
	v_pk_fma_f32 v[70:71], v[62:63], v[70:71], v[78:79] op_sel_hi:[0,1,1]
	v_mov_b32_e32 v81, v71
	v_pk_mul_f32 v[78:79], v[56:57], v[72:73] op_sel:[1,1] op_sel_hi:[1,0]
	v_pk_mul_f32 v[70:71], v[76:77], v[80:81] op_sel_hi:[0,1]
	v_pk_fma_f32 v[80:81], v[56:57], v[72:73], v[78:79] neg_lo:[0,0,1] neg_hi:[0,0,1]
	v_pk_fma_f32 v[72:73], v[56:57], v[72:73], v[78:79] op_sel_hi:[0,1,1]
	v_mov_b32_e32 v78, v59
	v_mov_b32_e32 v81, v73
	v_pk_mul_f32 v[78:79], v[78:79], v[74:75] op_sel:[0,1] op_sel_hi:[0,0]
	v_pk_mul_f32 v[72:73], v[76:77], v[80:81] op_sel_hi:[0,1]
	v_pk_fma_f32 v[80:81], v[58:59], v[74:75], v[78:79] neg_lo:[0,0,1] neg_hi:[0,0,1]
	v_pk_fma_f32 v[74:75], v[58:59], v[74:75], v[78:79] op_sel_hi:[0,1,1]
	v_mov_b32_e32 v81, v75
	v_pk_mul_f32 v[74:75], v[76:77], v[80:81] op_sel_hi:[0,1]
.LBB0_245:
	s_or_b64 exec, exec, s[34:35]
	v_ashrrev_i32_e32 v65, 31, v64
	v_lshlrev_b64 v[80:81], 13, v[64:65]
	v_cvt_pk_bf16_f32 v76, v68, v69
	v_lshl_add_u64 v[68:69], s[12:13], 0, v[80:81]
	v_cvt_pk_bf16_f32 v77, v70, v71
	v_lshl_add_u64 v[68:69], v[138:139], 1, v[68:69]
	v_or_b32_e32 v65, 0x80, v138
	v_cvt_pk_bf16_f32 v78, v72, v73
	v_cvt_pk_bf16_f32 v79, v74, v75
	global_store_dwordx4 v[68:69], v[76:79], off
	v_cmp_gt_i32_e32 vcc, s55, v65
	v_mov_b32_e32 v70, v52
	v_mov_b32_e32 v71, v53
	v_mov_b32_e32 v72, v54
	v_mov_b32_e32 v73, v55
	v_mov_b32_e32 v74, v48
	v_mov_b32_e32 v75, v49
	v_mov_b32_e32 v76, v50
	v_mov_b32_e32 v77, v51
	s_and_saveexec_b64 s[34:35], vcc
	s_cbranch_execz .LBB0_247
	v_and_b32_e32 v70, 0xf8, v65
	v_lshl_add_u64 v[66:67], s[14:15], 0, v[66:67]
	v_lshlrev_b32_e32 v138, 2, v70
	v_lshl_add_u64 v[66:67], v[66:67], 0, v[138:139]
	v_cmp_lt_i32_e32 vcc, s60, v65
	s_waitcnt vmcnt(1)
	v_mov_b32_e32 v74, v192
	v_mov_b32_e32 v75, v193
	v_mov_b32_e32 v76, v194
	v_mov_b32_e32 v77, v195
	v_mov_b32_e32 v70, v188
	v_mov_b32_e32 v71, v189
	v_mov_b32_e32 v72, v190
	v_mov_b32_e32 v73, v191
	v_pk_mul_f32 v[78:79], v[52:53], v[70:71] op_sel:[1,1] op_sel_hi:[1,0]
	s_nop 0
	v_pk_fma_f32 v[80:81], v[52:53], v[70:71], v[78:79] neg_lo:[0,0,1] neg_hi:[0,0,1]
	v_pk_fma_f32 v[70:71], v[52:53], v[70:71], v[78:79] op_sel_hi:[0,1,1]
	v_mov_b32_e32 v78, v55
	v_cndmask_b32_e32 v66, 1.0, v181, vcc
	v_mov_b32_e32 v81, v71
	v_pk_mul_f32 v[78:79], v[78:79], v[72:73] op_sel:[0,1] op_sel_hi:[0,0]
	v_pk_mul_f32 v[70:71], v[66:67], v[80:81] op_sel_hi:[0,1]
	v_pk_fma_f32 v[80:81], v[54:55], v[72:73], v[78:79] neg_lo:[0,0,1] neg_hi:[0,0,1]
	v_pk_fma_f32 v[72:73], v[54:55], v[72:73], v[78:79] op_sel_hi:[0,1,1]
	v_mov_b32_e32 v81, v73
	v_pk_mul_f32 v[78:79], v[48:49], v[74:75] op_sel:[1,1] op_sel_hi:[1,0]
	v_pk_mul_f32 v[72:73], v[66:67], v[80:81] op_sel_hi:[0,1]
	v_pk_fma_f32 v[80:81], v[48:49], v[74:75], v[78:79] neg_lo:[0,0,1] neg_hi:[0,0,1]
	v_pk_fma_f32 v[74:75], v[48:49], v[74:75], v[78:79] op_sel_hi:[0,1,1]
	v_mov_b32_e32 v78, v51
	v_mov_b32_e32 v81, v75
	v_pk_mul_f32 v[78:79], v[78:79], v[76:77] op_sel:[0,1] op_sel_hi:[0,0]
	v_pk_mul_f32 v[74:75], v[66:67], v[80:81] op_sel_hi:[0,1]
	v_pk_fma_f32 v[80:81], v[50:51], v[76:77], v[78:79] neg_lo:[0,0,1] neg_hi:[0,0,1]
	v_pk_fma_f32 v[76:77], v[50:51], v[76:77], v[78:79] op_sel_hi:[0,1,1]
	v_mov_b32_e32 v81, v77
	v_pk_mul_f32 v[76:77], v[66:67], v[80:81] op_sel_hi:[0,1]
.LBB0_247:
	s_waitcnt vmcnt(1)
	s_or_b64 exec, exec, s[34:35]
	v_cvt_pk_bf16_f32 v70, v70, v71
	v_cvt_pk_bf16_f32 v71, v72, v73
	v_cvt_pk_bf16_f32 v72, v74, v75
	v_cvt_pk_bf16_f32 v73, v76, v77
	global_store_dwordx4 v[68:69], v[70:73], off offset:256
	s_branch .LBB0_190

.LBB0_253:
	v_cmp_lt_i32_e32 vcc, s52, v48
	s_and_saveexec_b64 s[2:3], vcc
	s_xor_b64 s[34:35], exec, s[2:3]
	v_cmp_gt_u32_e32 vcc, s53, v48
	s_nop 1
	v_cndmask_b32_e32 v50, 0, v167, vcc
	s_andn2_saveexec_b64 s[34:35], s[34:35]
	v_mul_hi_i32 v49, v48, s54
	v_lshrrev_b32_e32 v50, 31, v49
	v_ashrrev_i32_e32 v49, 7, v49
	v_add_u32_e32 v49, v49, v50
	v_mul_lo_u32 v49, v49, s47
	v_sub_u32_e32 v50, v48, v49
	s_or_b64 exec, exec, s[34:35]
	v_lshl_add_u32 v138, s30, 8, v169
	v_ashrrev_i32_e32 v51, 31, v50
	v_lshlrev_b64 v[50:51], 10, v[50:51]
	v_cmp_gt_i32_e32 vcc, s55, v138
	v_mov_b32_e32 v52, v44
	v_mov_b32_e32 v53, v45
	v_mov_b32_e32 v54, v46
	v_mov_b32_e32 v55, v47
	v_mov_b32_e32 v56, v40
	v_mov_b32_e32 v57, v41
	v_mov_b32_e32 v58, v42
	v_mov_b32_e32 v59, v43
	s_and_saveexec_b64 s[34:35], vcc
	s_cbranch_execz .LBB0_259
	v_lshl_add_u64 v[52:53], v[140:141], 0, v[50:51]
	global_load_dwordx4 v[56:59], v[52:53], off offset:16
	s_nop 0
	global_load_dwordx4 v[52:55], v[52:53], off
	v_or_b32_e32 v200, 0x80, v138
	v_and_b32_e32 v200, 0xf8, v200
	v_mov_b32_e32 v201, 0
	v_lshlrev_b32_e32 v200, 2, v200
	v_lshl_add_u64 v[202:203], s[14:15], 0, v[50:51]
	v_lshl_add_u64 v[202:203], v[202:203], 0, v[200:201]
	global_load_dwordx4 v[192:195], v[202:203], off offset:16
	global_load_dwordx4 v[188:191], v[202:203], off
	v_cmp_lt_i32_e32 vcc, s60, v138
	s_waitcnt vmcnt(2)
	v_pk_mul_f32 v[62:63], v[44:45], v[52:53] op_sel:[1,1] op_sel_hi:[1,0]
	s_nop 0
	v_pk_fma_f32 v[64:65], v[44:45], v[52:53], v[62:63] neg_lo:[0,0,1] neg_hi:[0,0,1]
	v_pk_fma_f32 v[52:53], v[44:45], v[52:53], v[62:63] op_sel_hi:[0,1,1]
	v_mov_b32_e32 v62, v47
	v_cndmask_b32_e32 v60, 1.0, v181, vcc
	v_mov_b32_e32 v65, v53
	v_pk_mul_f32 v[62:63], v[62:63], v[54:55] op_sel:[0,1] op_sel_hi:[0,0]
	v_pk_mul_f32 v[52:53], v[60:61], v[64:65] op_sel_hi:[0,1]
	v_pk_fma_f32 v[64:65], v[46:47], v[54:55], v[62:63] neg_lo:[0,0,1] neg_hi:[0,0,1]
	v_pk_fma_f32 v[54:55], v[46:47], v[54:55], v[62:63] op_sel_hi:[0,1,1]
	v_mov_b32_e32 v65, v55
	v_pk_mul_f32 v[62:63], v[40:41], v[56:57] op_sel:[1,1] op_sel_hi:[1,0]
	v_pk_mul_f32 v[54:55], v[60:61], v[64:65] op_sel_hi:[0,1]
	v_pk_fma_f32 v[64:65], v[40:41], v[56:57], v[62:63] neg_lo:[0,0,1] neg_hi:[0,0,1]
	v_pk_fma_f32 v[56:57], v[40:41], v[56:57], v[62:63] op_sel_hi:[0,1,1]
	v_mov_b32_e32 v62, v43
	v_mov_b32_e32 v65, v57
	v_pk_mul_f32 v[62:63], v[62:63], v[58:59] op_sel:[0,1] op_sel_hi:[0,0]
	v_pk_mul_f32 v[56:57], v[60:61], v[64:65] op_sel_hi:[0,1]
	v_pk_fma_f32 v[64:65], v[42:43], v[58:59], v[62:63] neg_lo:[0,0,1] neg_hi:[0,0,1]
	v_pk_fma_f32 v[58:59], v[42:43], v[58:59], v[62:63] op_sel_hi:[0,1,1]
	v_mov_b32_e32 v65, v59
	v_pk_mul_f32 v[58:59], v[60:61], v[64:65] op_sel_hi:[0,1]
.LBB0_259:
	s_or_b64 exec, exec, s[34:35]
	v_ashrrev_i32_e32 v49, 31, v48
	v_lshlrev_b64 v[64:65], 13, v[48:49]
	v_cvt_pk_bf16_f32 v60, v52, v53
	v_lshl_add_u64 v[52:53], s[12:13], 0, v[64:65]
	v_cvt_pk_bf16_f32 v61, v54, v55
	v_lshl_add_u64 v[52:53], v[138:139], 1, v[52:53]
	v_or_b32_e32 v49, 0x80, v138
	v_cvt_pk_bf16_f32 v62, v56, v57
	v_cvt_pk_bf16_f32 v63, v58, v59
	global_store_dwordx4 v[52:53], v[60:63], off
	v_cmp_gt_i32_e32 vcc, s55, v49
	v_mov_b32_e32 v54, v36
	v_mov_b32_e32 v55, v37
	v_mov_b32_e32 v56, v38
	v_mov_b32_e32 v57, v39
	v_mov_b32_e32 v58, v32
	v_mov_b32_e32 v59, v33
	v_mov_b32_e32 v60, v34
	v_mov_b32_e32 v61, v35
	s_and_saveexec_b64 s[34:35], vcc
	s_cbranch_execz .LBB0_261
	v_and_b32_e32 v54, 0xf8, v49
	v_lshl_add_u64 v[50:51], s[14:15], 0, v[50:51]
	v_lshlrev_b32_e32 v138, 2, v54
	v_lshl_add_u64 v[50:51], v[50:51], 0, v[138:139]
	v_cmp_lt_i32_e32 vcc, s60, v49
	s_waitcnt vmcnt(1)
	v_mov_b32_e32 v58, v192
	v_mov_b32_e32 v59, v193
	v_mov_b32_e32 v60, v194
	v_mov_b32_e32 v61, v195
	v_mov_b32_e32 v54, v188
	v_mov_b32_e32 v55, v189
	v_mov_b32_e32 v56, v190
	v_mov_b32_e32 v57, v191
	v_pk_mul_f32 v[62:63], v[36:37], v[54:55] op_sel:[1,1] op_sel_hi:[1,0]
	s_nop 0
	v_pk_fma_f32 v[64:65], v[36:37], v[54:55], v[62:63] neg_lo:[0,0,1] neg_hi:[0,0,1]
	v_pk_fma_f32 v[54:55], v[36:37], v[54:55], v[62:63] op_sel_hi:[0,1,1]
	v_mov_b32_e32 v62, v39
	v_cndmask_b32_e32 v50, 1.0, v181, vcc
	v_mov_b32_e32 v65, v55
	v_pk_mul_f32 v[62:63], v[62:63], v[56:57] op_sel:[0,1] op_sel_hi:[0,0]
	v_pk_mul_f32 v[54:55], v[50:51], v[64:65] op_sel_hi:[0,1]
	v_pk_fma_f32 v[64:65], v[38:39], v[56:57], v[62:63] neg_lo:[0,0,1] neg_hi:[0,0,1]
	v_pk_fma_f32 v[56:57], v[38:39], v[56:57], v[62:63] op_sel_hi:[0,1,1]
	v_mov_b32_e32 v65, v57
	v_pk_mul_f32 v[62:63], v[32:33], v[58:59] op_sel:[1,1] op_sel_hi:[1,0]
	v_pk_mul_f32 v[56:57], v[50:51], v[64:65] op_sel_hi:[0,1]
	v_pk_fma_f32 v[64:65], v[32:33], v[58:59], v[62:63] neg_lo:[0,0,1] neg_hi:[0,0,1]
	v_pk_fma_f32 v[58:59], v[32:33], v[58:59], v[62:63] op_sel_hi:[0,1,1]
	v_mov_b32_e32 v62, v35
	v_mov_b32_e32 v65, v59
	v_pk_mul_f32 v[62:63], v[62:63], v[60:61] op_sel:[0,1] op_sel_hi:[0,0]
	v_pk_mul_f32 v[58:59], v[50:51], v[64:65] op_sel_hi:[0,1]
	v_pk_fma_f32 v[64:65], v[34:35], v[60:61], v[62:63] neg_lo:[0,0,1] neg_hi:[0,0,1]
	v_pk_fma_f32 v[60:61], v[34:35], v[60:61], v[62:63] op_sel_hi:[0,1,1]
	v_mov_b32_e32 v65, v61
	v_pk_mul_f32 v[60:61], v[50:51], v[64:65] op_sel_hi:[0,1]
.LBB0_261:
	s_waitcnt vmcnt(1)
	s_or_b64 exec, exec, s[34:35]
	v_cvt_pk_bf16_f32 v54, v54, v55
	v_cvt_pk_bf16_f32 v55, v56, v57
	v_cvt_pk_bf16_f32 v56, v58, v59
	v_cvt_pk_bf16_f32 v57, v60, v61
	global_store_dwordx4 v[52:53], v[54:57], off offset:256
	s_branch .LBB0_192

.LBB0_267:
	v_cmp_lt_i32_e32 vcc, s52, v32
	s_and_saveexec_b64 s[2:3], vcc
	s_xor_b64 s[34:35], exec, s[2:3]
	v_cmp_gt_u32_e32 vcc, s53, v32
	s_nop 1
	v_cndmask_b32_e32 v34, 0, v167, vcc
	s_andn2_saveexec_b64 s[34:35], s[34:35]
	v_mul_hi_i32 v33, v32, s54
	v_lshrrev_b32_e32 v34, 31, v33
	v_ashrrev_i32_e32 v33, 7, v33
	v_add_u32_e32 v33, v33, v34
	v_mul_lo_u32 v33, v33, s47
	v_sub_u32_e32 v34, v32, v33
	s_or_b64 exec, exec, s[34:35]
	v_lshl_add_u32 v138, s30, 8, v169
	v_ashrrev_i32_e32 v35, 31, v34
	v_lshlrev_b64 v[34:35], 10, v[34:35]
	v_cmp_gt_i32_e32 vcc, s55, v138
	v_mov_b32_e32 v36, v28
	v_mov_b32_e32 v37, v29
	v_mov_b32_e32 v38, v30
	v_mov_b32_e32 v39, v31
	v_mov_b32_e32 v40, v24
	v_mov_b32_e32 v41, v25
	v_mov_b32_e32 v42, v26
	v_mov_b32_e32 v43, v27
	s_and_saveexec_b64 s[34:35], vcc
	s_cbranch_execz .LBB0_273
	v_lshl_add_u64 v[36:37], v[140:141], 0, v[34:35]
	global_load_dwordx4 v[40:43], v[36:37], off offset:16
	s_nop 0
	global_load_dwordx4 v[36:39], v[36:37], off
	v_or_b32_e32 v200, 0x80, v138
	v_and_b32_e32 v200, 0xf8, v200
	v_mov_b32_e32 v201, 0
	v_lshlrev_b32_e32 v200, 2, v200
	v_lshl_add_u64 v[202:203], s[14:15], 0, v[34:35]
	v_lshl_add_u64 v[202:203], v[202:203], 0, v[200:201]
	global_load_dwordx4 v[192:195], v[202:203], off offset:16
	global_load_dwordx4 v[188:191], v[202:203], off
	v_cmp_lt_i32_e32 vcc, s60, v138
	s_waitcnt vmcnt(2)
	v_pk_mul_f32 v[46:47], v[28:29], v[36:37] op_sel:[1,1] op_sel_hi:[1,0]
	s_nop 0
	v_pk_fma_f32 v[48:49], v[28:29], v[36:37], v[46:47] neg_lo:[0,0,1] neg_hi:[0,0,1]
	v_pk_fma_f32 v[36:37], v[28:29], v[36:37], v[46:47] op_sel_hi:[0,1,1]
	v_mov_b32_e32 v46, v31
	v_cndmask_b32_e32 v44, 1.0, v181, vcc
	v_mov_b32_e32 v49, v37
	v_pk_mul_f32 v[46:47], v[46:47], v[38:39] op_sel:[0,1] op_sel_hi:[0,0]
	v_pk_mul_f32 v[36:37], v[44:45], v[48:49] op_sel_hi:[0,1]
	v_pk_fma_f32 v[48:49], v[30:31], v[38:39], v[46:47] neg_lo:[0,0,1] neg_hi:[0,0,1]
	v_pk_fma_f32 v[38:39], v[30:31], v[38:39], v[46:47] op_sel_hi:[0,1,1]
	v_mov_b32_e32 v49, v39
	v_pk_mul_f32 v[46:47], v[24:25], v[40:41] op_sel:[1,1] op_sel_hi:[1,0]
	v_pk_mul_f32 v[38:39], v[44:45], v[48:49] op_sel_hi:[0,1]
	v_pk_fma_f32 v[48:49], v[24:25], v[40:41], v[46:47] neg_lo:[0,0,1] neg_hi:[0,0,1]
	v_pk_fma_f32 v[40:41], v[24:25], v[40:41], v[46:47] op_sel_hi:[0,1,1]
	v_mov_b32_e32 v46, v27
	v_mov_b32_e32 v49, v41
	v_pk_mul_f32 v[46:47], v[46:47], v[42:43] op_sel:[0,1] op_sel_hi:[0,0]
	v_pk_mul_f32 v[40:41], v[44:45], v[48:49] op_sel_hi:[0,1]
	v_pk_fma_f32 v[48:49], v[26:27], v[42:43], v[46:47] neg_lo:[0,0,1] neg_hi:[0,0,1]
	v_pk_fma_f32 v[42:43], v[26:27], v[42:43], v[46:47] op_sel_hi:[0,1,1]
	v_mov_b32_e32 v49, v43
	v_pk_mul_f32 v[42:43], v[44:45], v[48:49] op_sel_hi:[0,1]
.LBB0_273:
	s_or_b64 exec, exec, s[34:35]
	v_ashrrev_i32_e32 v33, 31, v32
	v_lshlrev_b64 v[48:49], 13, v[32:33]
	v_cvt_pk_bf16_f32 v44, v36, v37
	v_lshl_add_u64 v[36:37], s[12:13], 0, v[48:49]
	v_cvt_pk_bf16_f32 v45, v38, v39
	v_lshl_add_u64 v[36:37], v[138:139], 1, v[36:37]
	v_or_b32_e32 v33, 0x80, v138
	v_cvt_pk_bf16_f32 v46, v40, v41
	v_cvt_pk_bf16_f32 v47, v42, v43
	global_store_dwordx4 v[36:37], v[44:47], off
	v_cmp_gt_i32_e32 vcc, s55, v33
	v_mov_b32_e32 v38, v20
	v_mov_b32_e32 v39, v21
	v_mov_b32_e32 v40, v22
	v_mov_b32_e32 v41, v23
	v_mov_b32_e32 v42, v16
	v_mov_b32_e32 v43, v17
	v_mov_b32_e32 v44, v18
	v_mov_b32_e32 v45, v19
	s_and_saveexec_b64 s[34:35], vcc
	s_cbranch_execz .LBB0_275
	v_and_b32_e32 v38, 0xf8, v33
	v_lshl_add_u64 v[34:35], s[14:15], 0, v[34:35]
	v_lshlrev_b32_e32 v138, 2, v38
	v_lshl_add_u64 v[34:35], v[34:35], 0, v[138:139]
	v_cmp_lt_i32_e32 vcc, s60, v33
	s_waitcnt vmcnt(1)
	v_mov_b32_e32 v42, v192
	v_mov_b32_e32 v43, v193
	v_mov_b32_e32 v44, v194
	v_mov_b32_e32 v45, v195
	v_mov_b32_e32 v38, v188
	v_mov_b32_e32 v39, v189
	v_mov_b32_e32 v40, v190
	v_mov_b32_e32 v41, v191
	v_pk_mul_f32 v[46:47], v[20:21], v[38:39] op_sel:[1,1] op_sel_hi:[1,0]
	s_nop 0
	v_pk_fma_f32 v[48:49], v[20:21], v[38:39], v[46:47] neg_lo:[0,0,1] neg_hi:[0,0,1]
	v_pk_fma_f32 v[38:39], v[20:21], v[38:39], v[46:47] op_sel_hi:[0,1,1]
	v_mov_b32_e32 v46, v23
	v_cndmask_b32_e32 v34, 1.0, v181, vcc
	v_mov_b32_e32 v49, v39
	v_pk_mul_f32 v[46:47], v[46:47], v[40:41] op_sel:[0,1] op_sel_hi:[0,0]
	v_pk_mul_f32 v[38:39], v[34:35], v[48:49] op_sel_hi:[0,1]
	v_pk_fma_f32 v[48:49], v[22:23], v[40:41], v[46:47] neg_lo:[0,0,1] neg_hi:[0,0,1]
	v_pk_fma_f32 v[40:41], v[22:23], v[40:41], v[46:47] op_sel_hi:[0,1,1]
	v_mov_b32_e32 v49, v41
	v_pk_mul_f32 v[46:47], v[16:17], v[42:43] op_sel:[1,1] op_sel_hi:[1,0]
	v_pk_mul_f32 v[40:41], v[34:35], v[48:49] op_sel_hi:[0,1]
	v_pk_fma_f32 v[48:49], v[16:17], v[42:43], v[46:47] neg_lo:[0,0,1] neg_hi:[0,0,1]
	v_pk_fma_f32 v[42:43], v[16:17], v[42:43], v[46:47] op_sel_hi:[0,1,1]
	v_mov_b32_e32 v46, v19
	v_mov_b32_e32 v49, v43
	v_pk_mul_f32 v[46:47], v[46:47], v[44:45] op_sel:[0,1] op_sel_hi:[0,0]
	v_pk_mul_f32 v[42:43], v[34:35], v[48:49] op_sel_hi:[0,1]
	v_pk_fma_f32 v[48:49], v[18:19], v[44:45], v[46:47] neg_lo:[0,0,1] neg_hi:[0,0,1]
	v_pk_fma_f32 v[44:45], v[18:19], v[44:45], v[46:47] op_sel_hi:[0,1,1]
	v_mov_b32_e32 v49, v45
	v_pk_mul_f32 v[44:45], v[34:35], v[48:49] op_sel_hi:[0,1]
.LBB0_275:
	s_waitcnt vmcnt(1)
	s_or_b64 exec, exec, s[34:35]
	v_cvt_pk_bf16_f32 v38, v38, v39
	v_cvt_pk_bf16_f32 v39, v40, v41
	v_cvt_pk_bf16_f32 v40, v42, v43
	v_cvt_pk_bf16_f32 v41, v44, v45
	global_store_dwordx4 v[36:37], v[38:41], off offset:256
	s_branch .LBB0_194

.LBB0_281:
	v_cmp_lt_i32_e32 vcc, s52, v16
	s_and_saveexec_b64 s[2:3], vcc
	s_xor_b64 s[6:7], exec, s[2:3]
	v_cmp_gt_u32_e32 vcc, s53, v16
	s_nop 1
	v_cndmask_b32_e32 v18, 0, v167, vcc
	s_andn2_saveexec_b64 s[6:7], s[6:7]
	v_mul_hi_i32 v17, v16, s54
	v_lshrrev_b32_e32 v18, 31, v17
	v_ashrrev_i32_e32 v17, 7, v17
	v_add_u32_e32 v17, v17, v18
	v_mul_lo_u32 v17, v17, s47
	v_sub_u32_e32 v18, v16, v17
	s_or_b64 exec, exec, s[6:7]
	v_lshl_add_u32 v138, s30, 8, v169
	v_ashrrev_i32_e32 v19, 31, v18
	v_lshlrev_b64 v[18:19], 10, v[18:19]
	v_cmp_gt_i32_e32 vcc, s55, v138
	v_mov_b32_e32 v20, v12
	v_mov_b32_e32 v21, v13
	v_mov_b32_e32 v22, v14
	v_mov_b32_e32 v23, v15
	v_mov_b32_e32 v24, v8
	v_mov_b32_e32 v25, v9
	v_mov_b32_e32 v26, v10
	v_mov_b32_e32 v27, v11
	s_and_saveexec_b64 s[6:7], vcc
	s_cbranch_execz .LBB0_287
	v_lshl_add_u64 v[20:21], v[140:141], 0, v[18:19]
	global_load_dwordx4 v[24:27], v[20:21], off offset:16
	s_nop 0
	global_load_dwordx4 v[20:23], v[20:21], off
	v_or_b32_e32 v200, 0x80, v138
	v_and_b32_e32 v200, 0xf8, v200
	v_mov_b32_e32 v201, 0
	v_lshlrev_b32_e32 v200, 2, v200
	v_lshl_add_u64 v[202:203], s[14:15], 0, v[18:19]
	v_lshl_add_u64 v[202:203], v[202:203], 0, v[200:201]
	global_load_dwordx4 v[192:195], v[202:203], off offset:16
	global_load_dwordx4 v[188:191], v[202:203], off
	v_cmp_lt_i32_e32 vcc, s60, v138
	s_waitcnt vmcnt(2)
	v_pk_mul_f32 v[30:31], v[12:13], v[20:21] op_sel:[1,1] op_sel_hi:[1,0]
	s_nop 0
	v_pk_fma_f32 v[32:33], v[12:13], v[20:21], v[30:31] neg_lo:[0,0,1] neg_hi:[0,0,1]
	v_pk_fma_f32 v[20:21], v[12:13], v[20:21], v[30:31] op_sel_hi:[0,1,1]
	v_mov_b32_e32 v30, v15
	v_cndmask_b32_e32 v28, 1.0, v181, vcc
	v_mov_b32_e32 v33, v21
	v_pk_mul_f32 v[30:31], v[30:31], v[22:23] op_sel:[0,1] op_sel_hi:[0,0]
	v_pk_mul_f32 v[20:21], v[28:29], v[32:33] op_sel_hi:[0,1]
	v_pk_fma_f32 v[32:33], v[14:15], v[22:23], v[30:31] neg_lo:[0,0,1] neg_hi:[0,0,1]
	v_pk_fma_f32 v[22:23], v[14:15], v[22:23], v[30:31] op_sel_hi:[0,1,1]
	v_mov_b32_e32 v33, v23
	v_pk_mul_f32 v[30:31], v[8:9], v[24:25] op_sel:[1,1] op_sel_hi:[1,0]
	v_pk_mul_f32 v[22:23], v[28:29], v[32:33] op_sel_hi:[0,1]
	v_pk_fma_f32 v[32:33], v[8:9], v[24:25], v[30:31] neg_lo:[0,0,1] neg_hi:[0,0,1]
	v_pk_fma_f32 v[24:25], v[8:9], v[24:25], v[30:31] op_sel_hi:[0,1,1]
	v_mov_b32_e32 v30, v11
	v_mov_b32_e32 v33, v25
	v_pk_mul_f32 v[30:31], v[30:31], v[26:27] op_sel:[0,1] op_sel_hi:[0,0]
	v_pk_mul_f32 v[24:25], v[28:29], v[32:33] op_sel_hi:[0,1]
	v_pk_fma_f32 v[32:33], v[10:11], v[26:27], v[30:31] neg_lo:[0,0,1] neg_hi:[0,0,1]
	v_pk_fma_f32 v[26:27], v[10:11], v[26:27], v[30:31] op_sel_hi:[0,1,1]
	v_mov_b32_e32 v33, v27
	v_pk_mul_f32 v[26:27], v[28:29], v[32:33] op_sel_hi:[0,1]
.LBB0_287:
	s_or_b64 exec, exec, s[6:7]
	v_ashrrev_i32_e32 v17, 31, v16
	v_lshlrev_b64 v[32:33], 13, v[16:17]
	v_cvt_pk_bf16_f32 v28, v20, v21
	v_lshl_add_u64 v[20:21], s[12:13], 0, v[32:33]
	v_cvt_pk_bf16_f32 v29, v22, v23
	v_lshl_add_u64 v[20:21], v[138:139], 1, v[20:21]
	v_or_b32_e32 v17, 0x80, v138
	v_cvt_pk_bf16_f32 v30, v24, v25
	v_cvt_pk_bf16_f32 v31, v26, v27
	global_store_dwordx4 v[20:21], v[28:31], off
	v_cmp_gt_i32_e32 vcc, s55, v17
	v_mov_b32_e32 v22, v4
	v_mov_b32_e32 v23, v5
	v_mov_b32_e32 v24, v6
	v_mov_b32_e32 v25, v7
	v_mov_b32_e32 v26, v0
	v_mov_b32_e32 v27, v1
	v_mov_b32_e32 v28, v2
	v_mov_b32_e32 v29, v3
	s_and_saveexec_b64 s[6:7], vcc
	s_cbranch_execz .LBB0_289
	v_and_b32_e32 v22, 0xf8, v17
	v_lshl_add_u64 v[18:19], s[14:15], 0, v[18:19]
	v_lshlrev_b32_e32 v138, 2, v22
	v_lshl_add_u64 v[18:19], v[18:19], 0, v[138:139]
	v_cmp_lt_i32_e32 vcc, s60, v17
	s_waitcnt vmcnt(1)
	v_mov_b32_e32 v26, v192
	v_mov_b32_e32 v27, v193
	v_mov_b32_e32 v28, v194
	v_mov_b32_e32 v29, v195
	v_mov_b32_e32 v22, v188
	v_mov_b32_e32 v23, v189
	v_mov_b32_e32 v24, v190
	v_mov_b32_e32 v25, v191
	v_pk_mul_f32 v[30:31], v[4:5], v[22:23] op_sel:[1,1] op_sel_hi:[1,0]
	s_nop 0
	v_pk_fma_f32 v[32:33], v[4:5], v[22:23], v[30:31] neg_lo:[0,0,1] neg_hi:[0,0,1]
	v_pk_fma_f32 v[22:23], v[4:5], v[22:23], v[30:31] op_sel_hi:[0,1,1]
	v_mov_b32_e32 v30, v7
	v_cndmask_b32_e32 v18, 1.0, v181, vcc
	v_mov_b32_e32 v33, v23
	v_pk_mul_f32 v[30:31], v[30:31], v[24:25] op_sel:[0,1] op_sel_hi:[0,0]
	v_pk_mul_f32 v[22:23], v[18:19], v[32:33] op_sel_hi:[0,1]
	v_pk_fma_f32 v[32:33], v[6:7], v[24:25], v[30:31] neg_lo:[0,0,1] neg_hi:[0,0,1]
	v_pk_fma_f32 v[24:25], v[6:7], v[24:25], v[30:31] op_sel_hi:[0,1,1]
	v_mov_b32_e32 v33, v25
	v_pk_mul_f32 v[30:31], v[0:1], v[26:27] op_sel:[1,1] op_sel_hi:[1,0]
	v_pk_mul_f32 v[24:25], v[18:19], v[32:33] op_sel_hi:[0,1]
	v_pk_fma_f32 v[32:33], v[0:1], v[26:27], v[30:31] neg_lo:[0,0,1] neg_hi:[0,0,1]
	v_pk_fma_f32 v[26:27], v[0:1], v[26:27], v[30:31] op_sel_hi:[0,1,1]
	v_mov_b32_e32 v30, v3
	v_mov_b32_e32 v33, v27
	v_pk_mul_f32 v[30:31], v[30:31], v[28:29] op_sel:[0,1] op_sel_hi:[0,0]
	v_pk_mul_f32 v[26:27], v[18:19], v[32:33] op_sel_hi:[0,1]
	v_pk_fma_f32 v[32:33], v[2:3], v[28:29], v[30:31] neg_lo:[0,0,1] neg_hi:[0,0,1]
	v_pk_fma_f32 v[28:29], v[2:3], v[28:29], v[30:31] op_sel_hi:[0,1,1]
	v_mov_b32_e32 v33, v29
	v_pk_mul_f32 v[28:29], v[18:19], v[32:33] op_sel_hi:[0,1]
.LBB0_289:
	s_waitcnt vmcnt(1)
	s_or_b64 exec, exec, s[6:7]
	v_cvt_pk_bf16_f32 v22, v22, v23
	v_cvt_pk_bf16_f32 v23, v24, v25
	v_cvt_pk_bf16_f32 v24, v26, v27
	v_cvt_pk_bf16_f32 v25, v28, v29
	global_store_dwordx4 v[20:21], v[22:25], off offset:256
	s_branch .LBB0_196
